# v9 + w_in_b transpose tile counts follow arrival rank at end of out-proj phase (10/9/7/6 tiles per rank quartile, one atomic per WG)
# speedup vs baseline: 1.0435x; 1.0062x over previous
;     __device__ __forceinline__ void fused(Acc& acc, const Unit& u, int wr, int wc, int fr, int fq, LAS unsigned char* lds, int wid, int lane) const {
;     ...
;         asm volatile("s_waitcnt vmcnt(0) lgkmcnt(0)" ::: "memory"); __builtin_amdgcn_s_barrier(); asm volatile("" ::: "memory");
;         if (lane < 32) {
;             const unsigned long long* slot = slots + (size_t)(u.pm * 256 + rowi) * 8; float S = 0.f, SS = 0.f;
; #pragma unroll
;             for (int t = 0; t < 8; ++t) { const unsigned long long w = __hip_atomic_load(slot + t, __ATOMIC_RELAXED, __HIP_MEMORY_SCOPE_AGENT); S += __uint_as_float((unsigned)w); SS += __uint_as_float((unsigned)(w >> 32)); }
;             const float mean = S * (1.0f / DM), var = SS * (1.0f / DM) - mean * mean;
;             St[rowi] = (f32x2){mean, rsqrtf(var + 1e-5f)};
;         }
.LBB0_362:
.LBB0_363:
	s_waitcnt vmcnt(0) lgkmcnt(0)
	s_barrier
	s_and_saveexec_b64 s[100:101], s[12:13]
	v_mov_b32_e32 v253, 0xa1c0
	v_mov_b32_e32 v254, 1
	global_atomic_add v255, v253, v254, s[54:55] sc0
	s_or_b64 exec, exec, s[100:101]
	s_and_saveexec_b64 s[6:7], s[4:5]
	s_cbranch_execz .LBB0_365
	v_lshlrev_b64 v[0:1], 6, v[0:1]
	v_lshl_add_u64 v[0:1], s[0:1], 0, v[0:1]
	global_load_dwordx2 v[4:5], v[0:1], off sc1
	global_load_dwordx2 v[6:7], v[0:1], off offset:8 sc1
	global_load_dwordx2 v[8:9], v[0:1], off offset:16 sc1
	global_load_dwordx2 v[10:11], v[0:1], off offset:24 sc1
	global_load_dwordx2 v[12:13], v[0:1], off offset:32 sc1
	global_load_dwordx2 v[14:15], v[0:1], off offset:40 sc1
	global_load_dwordx2 v[80:81], v[0:1], off offset:48 sc1
	s_nop 0
	global_load_dwordx2 v[0:1], v[0:1], off offset:56 sc1
	s_mov_b32 s0, 0x3a000000
	s_mov_b32 s1, 0x800000
	v_lshl_add_u32 v2, v2, 3, 0
	s_waitcnt vmcnt(7) lgkmcnt(0)
	v_add_f32_e32 v3, 0, v4
	s_waitcnt vmcnt(6)
	v_add_f32_e32 v3, v3, v6
	v_add_f32_e32 v4, 0, v5
	s_waitcnt vmcnt(5)
	v_add_f32_e32 v3, v3, v8
	v_add_f32_e32 v4, v4, v7
	s_waitcnt vmcnt(4)
	v_add_f32_e32 v3, v3, v10
	v_add_f32_e32 v4, v4, v9
	s_waitcnt vmcnt(3)
	v_add_f32_e32 v3, v3, v12
	v_add_f32_e32 v4, v4, v11
	s_waitcnt vmcnt(2)
	v_add_f32_e32 v3, v3, v14
	v_add_f32_e32 v4, v4, v13
	s_waitcnt vmcnt(1)
	v_add_f32_e32 v3, v3, v80
	v_add_f32_e32 v4, v4, v15
	s_waitcnt vmcnt(0)
	v_add_f32_e32 v0, v3, v0
	v_add_f32_e32 v4, v4, v81
	v_mul_f32_e32 v0, 0x3a000000, v0
	v_add_f32_e32 v1, v4, v1
	v_mul_f32_e32 v3, v0, v0
	v_fma_f32 v1, v1, s0, -v3
	v_add_f32_e32 v1, 0x3727c5ac, v1
	v_mul_f32_e32 v3, 0x4b800000, v1
	v_cmp_gt_f32_e32 vcc, s1, v1
	s_nop 1
	v_cndmask_b32_e32 v1, v1, v3, vcc
	v_rsq_f32_e32 v1, v1
	s_nop 0
	v_mul_f32_e32 v3, 0x45800000, v1
	v_cndmask_b32_e32 v1, v1, v3, vcc
	ds_write_b64 v2, v[0:1] offset:8192

; __device__ __forceinline__ unsigned xb_ld(unsigned* p)              { return __hip_atomic_load(p, __ATOMIC_RELAXED, __HIP_MEMORY_SCOPE_AGENT); }
; __device__ __forceinline__ unsigned xb_add(unsigned* p, unsigned v) { return __hip_atomic_fetch_add(p, v, __ATOMIC_RELAXED, __HIP_MEMORY_SCOPE_AGENT); }
; #define XB_SPIN(cond, bar) do { unsigned _sp = 0; while (cond) { __builtin_amdgcn_s_sleep(1); \
;     if ((++_sp & 255u) == 0u) { if (xb_ld(&(bar)[XB_TMO])) break; if (_sp > XB_SPIN_CAP) { atomicAdd(&(bar)[XB_TMO], 1u); break; } } } } while (0)
; __device__ __forceinline__ void xcd_barrier(const XcdBarrier& b) {
;     asm volatile("s_waitcnt vmcnt(0)" ::: "memory");
;     __syncthreads();
;     if (threadIdx.x == 0) {
;         unsigned* bar = b.bar;
;         __builtin_amdgcn_s_waitcnt(0);
;         unsigned nloc = b.st[0], nx = b.st[1];
;         if (nloc == 0u) { xcd_barrier_complete(bar, b.x, nloc, nx); b.st[0] = nloc; b.st[1] = nx; }
;         const unsigned old = xb_add(&bar[XB_XSUB(b.x)], 1u);
;         const unsigned gen = old / nloc;
;         if (old + 1u == (gen + 1u) * nloc) {
;             __builtin_amdgcn_fence(__ATOMIC_RELEASE, "agent");
;             asm volatile("s_waitcnt vmcnt(0)" ::: "memory");
;             const unsigned og = xb_add(&bar[XB_TOP], 1u);
;             const unsigned tg = og / nx;
;             if (og + 1u == (tg + 1u) * nx) xb_add(&bar[XB_TOPGEN], 1u);
;             else XB_SPIN(xb_ld(&bar[XB_TOPGEN]) == tg, bar);
;             __builtin_amdgcn_fence(__ATOMIC_ACQUIRE, "agent");
;             xb_add(&bar[XB_XGEN(b.x)], 1u);
;             asm volatile("s_waitcnt vmcnt(0)" ::: "memory");
;         } else {
;             XB_SPIN(xb_ld(&bar[XB_XGEN(b.x)]) == gen, bar);
;             __builtin_amdgcn_fence(__ATOMIC_ACQUIRE, "agent");
;             asm volatile("s_waitcnt vmcnt(0)" ::: "memory");
;         }
;     }
;     __syncthreads();
; }
.LBB0_366:
	s_cmp_gt_u32 s43, 4
	s_cselect_b64 s[0:1], -1, 0
	s_and_b64 s[0:1], s[16:17], s[0:1]
	s_andn2_b64 vcc, exec, s[0:1]
	s_cbranch_vccnz .LBB0_416
	s_waitcnt vmcnt(0)
	s_waitcnt vmcnt(0) lgkmcnt(0)
	s_barrier
	s_and_saveexec_b64 s[0:1], s[12:13]
	s_cbranch_execz .LBB0_415
	s_and_b32 s98, s2, 7
	s_lshl_b32 s98, s98, 2
	s_bfe_u32 s99, s2, 0x20003
	s_or_b32 s98, s98, s99
	s_lshl_b32 s98, s98, 6
	s_add_i32 s98, s98, 0xa400
	v_mov_b32_e32 v250, s98
	v_mov_b32_e32 v252, 1
	v_mov_b32_e32 v253, 0x20008
	ds_write_b32 v253, v255
	v_mov_b32_e32 v253, 0x2000c
	ds_read_b32 v254, v253
	s_waitcnt lgkmcnt(0)
	v_readfirstlane_b32 s99, v254
	s_cmp_eq_u32 s99, 1
	s_cbranch_scc1 .Lpb3_fast
	buffer_wbl2 sc1
	s_waitcnt vmcnt(0)

; #define LAS __attribute__((address_space(3)))
; template <bool REMAP = false>
; __device__ __forceinline__ void transpose_convert(LAS unsigned char* lds, const float* src, bf16_t* dst, int K, int N, int G, int bid) {
;     LAS float* tile = (LAS float*)lds;
;     const int tid = threadIdx.x, ntn = N / 64, ntiles = (K / 128) * ntn;
;     const int r0 = tid >> 4, c4 = tid & 15;
;     f32x4 v[4];
;     if (bid < ntiles) { const int k0 = (bid / ntn) * 128, n0 = (bid % ntn) * 64;
; #pragma unroll
;         for (int i = 0; i < 4; ++i) v[i] = __builtin_nontemporal_load((const f32x4*)(src + (size_t)(k0 + r0 + 32 * i) * N + n0 + c4 * 4)); }
; __global__ void __launch_bounds__(NTHREADS, 2) mk_fwd(Params P) {
;     ...
;         transpose_convert(lds, P.w_in_b, WINB, 2048, 8192, G, bid);
.LBB0_416:
	s_cmp_lt_i32 s42, 6
	s_cselect_b64 s[0:1], -1, 0
	s_cmp_gt_i32 s43, 5
	s_cselect_b64 s[4:5], -1, 0
	s_and_b64 s[0:1], s[0:1], s[4:5]
	s_andn2_b64 vcc, exec, s[0:1]
	s_cbranch_vccnz .LBB0_448
	v_and_b32_e32 v20, 15, v164
	v_mov_b32_e32 v46, 0x20008
	ds_read_b32 v48, v46
	s_waitcnt lgkmcnt(0)
	v_readfirstlane_b32 s99, v48
	s_and_b32 s99, s99, 0xff
	s_lshr_b32 s3, s99, 6
	s_and_b32 s4, s99, 63
	s_mov_b32 s100, 10
	s_mov_b32 s5, 0
	s_cmp_lt_u32 s3, 1
	s_cbranch_scc1 .Lrk5_done
	s_mov_b32 s100, 9
	s_movk_i32 s5, 640
	s_cmp_lt_u32 s3, 2
	s_cbranch_scc1 .Lrk5_done
	s_mov_b32 s100, 7
	s_movk_i32 s5, 1216
	s_cmp_lt_u32 s3, 3
	s_cbranch_scc1 .Lrk5_done
	s_mov_b32 s100, 6
	s_movk_i32 s5, 1664
.Lrk5_done:
	s_mul_i32 s4, s4, s100
	s_add_i32 s99, s5, s4
	s_add_i32 s100, s99, s100
	s_ashr_i32 s3, s99, 31
	s_lshr_b32 s3, s3, 25
	s_add_i32 s3, s99, s3
	s_and_b32 s3, s3, 0xffffff80
	s_sub_i32 s4, s99, s3
	s_lshl_b32 s4, s4, 6
	s_ashr_i32 s5, s4, 31
	s_lshl_b64 s[4:5], s[4:5], 2
	s_waitcnt vmcnt(0)
	v_or_b32_e32 v8, s3, v214
	s_add_u32 s4, s30, s4
	s_addc_u32 s5, s31, s5
	v_lshlrev_b32_e32 v18, 4, v20
	v_mov_b32_e32 v19, 0
	v_ashrrev_i32_e32 v9, 31, v8
	v_lshl_add_u64 v[10:11], s[4:5], 0, v[18:19]
	v_lshlrev_b64 v[0:1], 15, v[8:9]
	v_lshl_add_u64 v[12:13], v[10:11], 0, v[0:1]
	s_mov_b32 s3, 0x100000
	v_or_b32_e32 v8, 64, v8
	v_add_co_u32_e32 v14, vcc, s3, v12
	v_ashrrev_i32_e32 v9, 31, v8
	s_nop 0
	v_addc_co_u32_e32 v15, vcc, 0, v13, vcc
	v_lshlrev_b64 v[8:9], 15, v[8:9]
	s_mov_b32 s16, 0x300000
	v_lshl_add_u64 v[16:17], v[10:11], 0, v[8:9]
	v_add_co_u32_e32 v22, vcc, s16, v12
	global_load_dwordx4 v[0:3], v[12:13], off nt
	global_load_dwordx4 v[4:7], v[14:15], off nt
	v_addc_co_u32_e32 v23, vcc, 0, v13, vcc
	global_load_dwordx4 v[8:11], v[16:17], off nt
	global_load_dwordx4 v[12:15], v[22:23], off nt
	v_add_u32_e32 v21, 0x200, v164
	v_add_u32_e32 v22, 0, v18
	v_lshrrev_b32_e32 v21, 4, v21
	v_mul_u32_u24_e32 v23, 0x104, v214
	v_lshl_add_u32 v27, v21, 2, 0
	v_mul_u32_u24_e32 v28, 0x820, v20
	v_lshl_add_u32 v26, v214, 2, 0
	v_add_u32_e32 v22, v22, v23
	v_lshl_add_u64 v[16:17], s[30:31], 0, v[18:19]
	v_lshl_add_u64 v[18:19], s[40:41], 0, v[18:19]
	s_lshl_b32 s18, s99, 6
	s_movk_i32 s17, 64
	v_add_u32_e32 v23, 0x2080, v22
	v_add_u32_e32 v24, 0x2088, v22
	v_add_u32_e32 v25, 0x4100, v22
	v_add_u32_e32 v26, v26, v28
	v_add_u32_e32 v27, v27, v28
	v_add_u32_e32 v28, 0x4108, v22
	v_add_u32_e32 v29, 0x6180, v22
	s_mov_b32 s19, s99
	s_branch .LBB0_420

; template <bool REMAP = false>
; __device__ __forceinline__ void transpose_convert(LAS unsigned char* lds, const float* src, bf16_t* dst, int K, int N, int G, int bid) {
;     ...
;     for (int t = bid; t < ntiles; t += G) {
;         const int k0 = (t / ntn) * 128, n0 = (t % ntn) * 64;
;         asm volatile("s_waitcnt lgkmcnt(0)" ::: "memory"); __builtin_amdgcn_s_barrier(); asm volatile("" ::: "memory");
; #pragma unroll
;         for (int i = 0; i < 4; ++i) {
; #pragma unroll
;             for (int j = 0; j < 4; ++j) tile[(r0 + 32 * i) * 65 + c4 * 4 + j] = v[i][j]; }
;         asm volatile("s_waitcnt lgkmcnt(0)" ::: "memory"); __builtin_amdgcn_s_barrier(); asm volatile("" ::: "memory");
;         if (t + G < ntiles) { const int k1 = ((t + G) / ntn) * 128, n1 = ((t + G) % ntn) * 64;
; #pragma unroll
;             for (int i = 0; i < 4; ++i) v[i] = __builtin_nontemporal_load((const f32x4*)(src + (size_t)(k1 + r0 + 32 * i) * N + n1 + c4 * 4)); }
.LBB0_420:
	s_nop 0
	v_add_u32_e32 v30, 0x6188, v22
	s_waitcnt lgkmcnt(0)
	s_barrier
	s_waitcnt vmcnt(3)
	ds_write2_b32 v22, v0, v1 offset1:1
	ds_write2_b32 v22, v2, v3 offset0:2 offset1:3
	s_waitcnt vmcnt(2)
	ds_write2_b32 v23, v4, v5 offset1:1
	ds_write2_b32 v24, v6, v7 offset1:1
	s_waitcnt vmcnt(1)
	ds_write2_b32 v25, v8, v9 offset1:1
	ds_write2_b32 v28, v10, v11 offset1:1
	s_waitcnt vmcnt(0)
	ds_write2_b32 v29, v12, v13 offset1:1
	ds_write2_b32 v30, v14, v15 offset1:1
	s_waitcnt lgkmcnt(0)
	s_barrier
	s_add_i32 s22, s19, 1
	s_cmp_ge_i32 s22, s100
	s_cselect_b64 s[4:5], -1, 0
	s_cmp_lt_i32 s22, s100
	s_mov_b64 s[6:7], -1
	s_cbranch_scc1 .LBB0_422
	s_add_i32 s23, s18, s17
	s_mov_b64 s[6:7], 0
